# combo8 + s_setprio 1 while QK MFMAs issue in all attention tiles
# baseline (speedup 1.0000x reference)
; #define MFMA(a, b, c) __builtin_amdgcn_mfma_f32_32x32x16_bf16((a), (b), (c), 0, 0, 0)
; DI int crow(int r, int hi) { return (r & 3) + 8 * (r >> 2) + 4 * hi; }
; template <class MaskF>
; DI void attn_tile(const int tid, const char* ldsK, const char* ldsV, const bf16x8 (&qr)[4], f32x16 (&o)[2], float& m, float& l, const bool MASKED, MaskF mask) {
;     ...
;   const char* kp = ldsK + l31 * 144 + hi * 16;
; #pragma unroll
;   for (int s = 0; s < 4; ++s) {
;     const bf16x8 k0 = *(const bf16x8*)(kp + s * 32), k1 = *(const bf16x8*)(kp + 32 * 144 + s * 32);
;     p0 = MFMA(k0, qr[s], p0); p1 = MFMA(k1, qr[s], p1);
;   }
;   if (MASKED) {
; #pragma unroll
;     for (int r = 0; r < 16; ++r) {
;       const int kr = crow(r, hi);
;       p0[r] = mask(kr) ? p0[r] : NEGB; p1[r] = mask(kr + 32) ? p1[r] : NEGB;
;     }
;   }
; DI void win_item(const Params& p, int it, char* lds) {
;     ...
;               [&](int ti, int kr) { return (unsigned)(t - ((klo + ti) * 64 + kr)) <= 511u; },
.LBB0_236:
	ds_read_b128 v[32:35], v160 offset:4608
	ds_read_b128 v[36:39], v160
	ds_read_b128 v[112:115], v160 offset:32
	ds_read_b128 v[116:119], v160 offset:4640
	ds_read_b128 v[120:123], v160 offset:64
	ds_read_b128 v[124:127], v160 offset:4672
	ds_read_b128 v[128:131], v160 offset:96
	ds_read_b128 v[132:135], v160 offset:4704
	s_add_i32 s11, s4, 0xffffff81
	s_sub_i32 s2, s4, 64
	s_waitcnt lgkmcnt(6)
	s_setprio 1
	v_mfma_f32_32x32x16_bf16 v[48:63], v[36:39], v[64:67], 0
	s_cmp_gt_u32 s2, s9
	s_cselect_b64 s[2:3], -1, 0
	s_cmp_lt_i32 s11, s6
	s_cselect_b64 s[12:13], -1, 0
	s_or_b64 s[2:3], s[2:3], s[12:13]
	s_andn2_b64 vcc, exec, s[2:3]
	v_mfma_f32_32x32x16_bf16 v[32:47], v[32:35], v[64:67], 0
	s_waitcnt lgkmcnt(5)
	v_mfma_f32_32x32x16_bf16 v[48:63], v[112:115], v[68:71], v[48:63]
	s_waitcnt lgkmcnt(4)
	v_mfma_f32_32x32x16_bf16 v[32:47], v[116:119], v[68:71], v[32:47]
	s_waitcnt lgkmcnt(3)
	v_mfma_f32_32x32x16_bf16 v[48:63], v[120:123], v[72:75], v[48:63]
	s_waitcnt lgkmcnt(2)
	v_mfma_f32_32x32x16_bf16 v[32:47], v[124:127], v[72:75], v[32:47]
	s_waitcnt lgkmcnt(1)
	v_mfma_f32_32x32x16_bf16 v[48:63], v[128:131], v[76:79], v[48:63]
	s_waitcnt lgkmcnt(0)
	v_mfma_f32_32x32x16_bf16 v[32:47], v[132:135], v[76:79], v[32:47]
	s_setprio 0
	s_cbranch_vccnz .LBB0_238
	v_add_u32_e32 v112, v148, v155
	v_cmp_gt_u32_e32 vcc, s72, v112
	v_subrev_u32_e32 v113, 32, v112
	s_nop 5
	v_cndmask_b32_e32 v48, v194, v48, vcc
	v_cmp_gt_u32_e32 vcc, s72, v113
	v_add_u32_e32 v113, -1, v112
	s_nop 0
	v_cndmask_b32_e32 v32, v194, v32, vcc
	v_cmp_gt_u32_e32 vcc, s72, v113
	v_subrev_u32_e32 v113, 33, v112
	s_nop 0
	v_cndmask_b32_e32 v49, v194, v49, vcc
	v_cmp_gt_u32_e32 vcc, s72, v113
	v_add_u32_e32 v113, -2, v112
	s_nop 0
	v_cndmask_b32_e32 v33, v194, v33, vcc
	v_cmp_gt_u32_e32 vcc, s72, v113
	v_subrev_u32_e32 v113, 34, v112
	s_nop 0
	v_cndmask_b32_e32 v50, v194, v50, vcc
	v_cmp_gt_u32_e32 vcc, s72, v113
	v_add_u32_e32 v113, -3, v112
	s_nop 0
	v_cndmask_b32_e32 v34, v194, v34, vcc
	v_cmp_gt_u32_e32 vcc, s72, v113
	v_subrev_u32_e32 v113, 35, v112
	s_nop 0
	v_cndmask_b32_e32 v51, v194, v51, vcc
	v_cmp_gt_u32_e32 vcc, s72, v113
	v_add_u32_e32 v113, -8, v112
	s_nop 0
	v_cndmask_b32_e32 v35, v194, v35, vcc
	v_cmp_gt_u32_e32 vcc, s72, v113
	v_subrev_u32_e32 v113, 40, v112
	s_nop 0
	v_cndmask_b32_e32 v52, v194, v52, vcc
	v_cmp_gt_u32_e32 vcc, s72, v113
	v_add_u32_e32 v113, -9, v112
	s_nop 0
	v_cndmask_b32_e32 v36, v194, v36, vcc
	v_cmp_gt_u32_e32 vcc, s72, v113
	v_subrev_u32_e32 v113, 41, v112
	s_nop 0
	v_cndmask_b32_e32 v53, v194, v53, vcc
	v_cmp_gt_u32_e32 vcc, s72, v113
	v_add_u32_e32 v113, -10, v112
	s_nop 0
	v_cndmask_b32_e32 v37, v194, v37, vcc
	v_cmp_gt_u32_e32 vcc, s72, v113
	v_subrev_u32_e32 v113, 42, v112
	s_nop 0
	v_cndmask_b32_e32 v54, v194, v54, vcc
	v_cmp_gt_u32_e32 vcc, s72, v113
	v_add_u32_e32 v113, -11, v112
	s_nop 0
	v_cndmask_b32_e32 v38, v194, v38, vcc
	v_cmp_gt_u32_e32 vcc, s72, v113
	v_subrev_u32_e32 v113, 43, v112
	s_nop 0
	v_cndmask_b32_e32 v55, v194, v55, vcc
	v_cmp_gt_u32_e32 vcc, s72, v113
	v_add_u32_e32 v113, -16, v112
	s_nop 0
	v_cndmask_b32_e32 v39, v194, v39, vcc
	v_cmp_gt_u32_e32 vcc, s72, v113
	v_subrev_u32_e32 v113, 48, v112
	s_nop 0
	v_cndmask_b32_e32 v56, v194, v56, vcc
	v_cmp_gt_u32_e32 vcc, s72, v113
	v_subrev_u32_e32 v113, 17, v112
	s_nop 0
	v_cndmask_b32_e32 v40, v194, v40, vcc
	v_cmp_gt_u32_e32 vcc, s72, v113
	v_subrev_u32_e32 v113, 49, v112
	s_nop 0
	v_cndmask_b32_e32 v57, v194, v57, vcc
	v_cmp_gt_u32_e32 vcc, s72, v113
	v_subrev_u32_e32 v113, 18, v112
	s_nop 0
	v_cndmask_b32_e32 v41, v194, v41, vcc
	v_cmp_gt_u32_e32 vcc, s72, v113
	v_subrev_u32_e32 v113, 50, v112
	s_nop 0
	v_cndmask_b32_e32 v58, v194, v58, vcc
	v_cmp_gt_u32_e32 vcc, s72, v113
	v_subrev_u32_e32 v113, 19, v112
	s_nop 0
	v_cndmask_b32_e32 v42, v194, v42, vcc
	v_cmp_gt_u32_e32 vcc, s72, v113
	v_subrev_u32_e32 v113, 51, v112
	s_nop 0
	v_cndmask_b32_e32 v59, v194, v59, vcc
	v_cmp_gt_u32_e32 vcc, s72, v113
	v_subrev_u32_e32 v113, 24, v112
	s_nop 0
	v_cndmask_b32_e32 v43, v194, v43, vcc
	v_cmp_gt_u32_e32 vcc, s72, v113
	v_subrev_u32_e32 v113, 56, v112
	s_nop 0
	v_cndmask_b32_e32 v60, v194, v60, vcc
	v_cmp_gt_u32_e32 vcc, s72, v113
	v_subrev_u32_e32 v113, 25, v112
	s_nop 0
	v_cndmask_b32_e32 v44, v194, v44, vcc
	v_cmp_gt_u32_e32 vcc, s72, v113
	v_subrev_u32_e32 v113, 57, v112
	s_nop 0
	v_cndmask_b32_e32 v61, v194, v61, vcc
	v_cmp_gt_u32_e32 vcc, s72, v113
	v_subrev_u32_e32 v113, 26, v112
	s_nop 0
	v_cndmask_b32_e32 v45, v194, v45, vcc
	v_cmp_gt_u32_e32 vcc, s72, v113
	v_subrev_u32_e32 v113, 58, v112
	s_nop 0
	v_cndmask_b32_e32 v62, v194, v62, vcc
	v_cmp_gt_u32_e32 vcc, s72, v113
	v_subrev_u32_e32 v113, 27, v112
	v_subrev_u32_e32 v112, 59, v112
	v_cndmask_b32_e32 v46, v194, v46, vcc
	v_cmp_gt_u32_e32 vcc, s72, v113
	s_nop 1
	v_cndmask_b32_e32 v63, v194, v63, vcc
	v_cmp_gt_u32_e32 vcc, s72, v112
	s_nop 1
	v_cndmask_b32_e32 v47, v194, v47, vcc

; #define MFMA(a, b, c) __builtin_amdgcn_mfma_f32_32x32x16_bf16((a), (b), (c), 0, 0, 0)
; DI int crow(int r, int hi) { return (r & 3) + 8 * (r >> 2) + 4 * hi; }
; template <class MaskF>
; DI void attn_tile(const int tid, const char* ldsK, const char* ldsV, const bf16x8 (&qr)[4], f32x16 (&o)[2], float& m, float& l, const bool MASKED, MaskF mask) {
;     ...
;   const char* kp = ldsK + l31 * 144 + hi * 16;
; #pragma unroll
;   for (int s = 0; s < 4; ++s) {
;     const bf16x8 k0 = *(const bf16x8*)(kp + s * 32), k1 = *(const bf16x8*)(kp + 32 * 144 + s * 32);
;     p0 = MFMA(k0, qr[s], p0); p1 = MFMA(k1, qr[s], p1);
;   }
;   if (MASKED) {
; #pragma unroll
;     for (int r = 0; r < 16; ++r) {
;       const int kr = crow(r, hi);
;       p0[r] = mask(kr) ? p0[r] : NEGB; p1[r] = mask(kr + 32) ? p1[r] : NEGB;
;     }
;   }
; DI void win_item(const Params& p, int it, char* lds) {
;     ...
;               [&](int ti, int kr) { return (unsigned)(t - ((klo + ti) * 64 + kr)) <= 511u; },
.LBB0_243:
	ds_read_b128 v[32:35], v160 offset:23040
	ds_read_b128 v[36:39], v160 offset:18432
	ds_read_b128 v[112:115], v160 offset:18464
	ds_read_b128 v[116:119], v160 offset:23072
	ds_read_b128 v[120:123], v160 offset:18496
	ds_read_b128 v[124:127], v160 offset:23104
	ds_read_b128 v[128:131], v160 offset:18528
	ds_read_b128 v[132:135], v160 offset:23136
	s_sub_i32 s11, s4, 63
	s_cmp_gt_u32 s4, s9
	s_waitcnt lgkmcnt(6)
	s_setprio 1
	v_mfma_f32_32x32x16_bf16 v[48:63], v[36:39], v[64:67], 0
	s_cselect_b64 s[2:3], -1, 0
	s_cmp_lt_i32 s11, s6
	s_cselect_b64 s[12:13], -1, 0
	s_or_b64 s[2:3], s[2:3], s[12:13]
	s_andn2_b64 vcc, exec, s[2:3]
	v_mfma_f32_32x32x16_bf16 v[32:47], v[32:35], v[64:67], 0
	s_waitcnt lgkmcnt(5)
	v_mfma_f32_32x32x16_bf16 v[48:63], v[112:115], v[68:71], v[48:63]
	s_waitcnt lgkmcnt(4)
	v_mfma_f32_32x32x16_bf16 v[32:47], v[116:119], v[68:71], v[32:47]
	s_waitcnt lgkmcnt(3)
	v_mfma_f32_32x32x16_bf16 v[48:63], v[120:123], v[72:75], v[48:63]
	s_waitcnt lgkmcnt(2)
	v_mfma_f32_32x32x16_bf16 v[32:47], v[124:127], v[72:75], v[32:47]
	s_waitcnt lgkmcnt(1)
	v_mfma_f32_32x32x16_bf16 v[48:63], v[128:131], v[76:79], v[48:63]
	s_waitcnt lgkmcnt(0)
	v_mfma_f32_32x32x16_bf16 v[32:47], v[132:135], v[76:79], v[32:47]
	s_setprio 0
	s_cbranch_vccnz .LBB0_245
	v_add_u32_e32 v112, v148, v154
	v_subrev_u32_e32 v113, 64, v112
	v_cmp_gt_u32_e32 vcc, s72, v113
	v_add_u32_e32 v113, 0xffffffa0, v112
	s_nop 4
	v_cndmask_b32_e32 v48, v194, v48, vcc
	v_cmp_gt_u32_e32 vcc, s72, v113
	v_add_u32_e32 v113, 0xffffffbf, v112
	s_nop 0
	v_cndmask_b32_e32 v32, v194, v32, vcc
	v_cmp_gt_u32_e32 vcc, s72, v113
	v_add_u32_e32 v113, 0xffffff9f, v112
	s_nop 0
	v_cndmask_b32_e32 v49, v194, v49, vcc
	v_cmp_gt_u32_e32 vcc, s72, v113
	v_add_u32_e32 v113, 0xffffffbe, v112
	s_nop 0
	v_cndmask_b32_e32 v33, v194, v33, vcc
	v_cmp_gt_u32_e32 vcc, s72, v113
	v_add_u32_e32 v113, 0xffffff9e, v112
	s_nop 0
	v_cndmask_b32_e32 v50, v194, v50, vcc
	v_cmp_gt_u32_e32 vcc, s72, v113
	v_add_u32_e32 v113, 0xffffffbd, v112
	s_nop 0
	v_cndmask_b32_e32 v34, v194, v34, vcc
	v_cmp_gt_u32_e32 vcc, s72, v113
	v_add_u32_e32 v113, 0xffffff9d, v112
	s_nop 0
	v_cndmask_b32_e32 v51, v194, v51, vcc
	v_cmp_gt_u32_e32 vcc, s72, v113
	v_add_u32_e32 v113, 0xffffffb8, v112
	s_nop 0
	v_cndmask_b32_e32 v35, v194, v35, vcc
	v_cmp_gt_u32_e32 vcc, s72, v113
	v_add_u32_e32 v113, 0xffffff98, v112
	s_nop 0
	v_cndmask_b32_e32 v52, v194, v52, vcc
	v_cmp_gt_u32_e32 vcc, s72, v113
	v_add_u32_e32 v113, 0xffffffb7, v112
	s_nop 0
	v_cndmask_b32_e32 v36, v194, v36, vcc
	v_cmp_gt_u32_e32 vcc, s72, v113
	v_add_u32_e32 v113, 0xffffff97, v112
	s_nop 0
	v_cndmask_b32_e32 v53, v194, v53, vcc
	v_cmp_gt_u32_e32 vcc, s72, v113
	v_add_u32_e32 v113, 0xffffffb6, v112
	s_nop 0
	v_cndmask_b32_e32 v37, v194, v37, vcc
	v_cmp_gt_u32_e32 vcc, s72, v113
	v_add_u32_e32 v113, 0xffffff96, v112
	s_nop 0
	v_cndmask_b32_e32 v54, v194, v54, vcc
	v_cmp_gt_u32_e32 vcc, s72, v113
	v_add_u32_e32 v113, 0xffffffb5, v112
	s_nop 0
	v_cndmask_b32_e32 v38, v194, v38, vcc
	v_cmp_gt_u32_e32 vcc, s72, v113
	v_add_u32_e32 v113, 0xffffff95, v112
	s_nop 0
	v_cndmask_b32_e32 v55, v194, v55, vcc
	v_cmp_gt_u32_e32 vcc, s72, v113
	v_add_u32_e32 v113, 0xffffffb0, v112
	s_nop 0
	v_cndmask_b32_e32 v39, v194, v39, vcc
	v_cmp_gt_u32_e32 vcc, s72, v113
	v_add_u32_e32 v113, 0xffffff90, v112
	s_nop 0
	v_cndmask_b32_e32 v56, v194, v56, vcc
	v_cmp_gt_u32_e32 vcc, s72, v113
	v_add_u32_e32 v113, 0xffffffaf, v112
	s_nop 0
	v_cndmask_b32_e32 v40, v194, v40, vcc
	v_cmp_gt_u32_e32 vcc, s72, v113
	v_add_u32_e32 v113, 0xffffff8f, v112
	s_nop 0
	v_cndmask_b32_e32 v57, v194, v57, vcc
	v_cmp_gt_u32_e32 vcc, s72, v113
	v_add_u32_e32 v113, 0xffffffae, v112
	s_nop 0
	v_cndmask_b32_e32 v41, v194, v41, vcc
	v_cmp_gt_u32_e32 vcc, s72, v113
	v_add_u32_e32 v113, 0xffffff8e, v112
	s_nop 0
	v_cndmask_b32_e32 v58, v194, v58, vcc
	v_cmp_gt_u32_e32 vcc, s72, v113
	v_add_u32_e32 v113, 0xffffffad, v112
	s_nop 0
	v_cndmask_b32_e32 v42, v194, v42, vcc
	v_cmp_gt_u32_e32 vcc, s72, v113
	v_add_u32_e32 v113, 0xffffff8d, v112
	s_nop 0
	v_cndmask_b32_e32 v59, v194, v59, vcc
	v_cmp_gt_u32_e32 vcc, s72, v113
	v_add_u32_e32 v113, 0xffffffa8, v112
	s_nop 0
	v_cndmask_b32_e32 v43, v194, v43, vcc
	v_cmp_gt_u32_e32 vcc, s72, v113
	v_add_u32_e32 v113, 0xffffff88, v112
	s_nop 0
	v_cndmask_b32_e32 v60, v194, v60, vcc
	v_cmp_gt_u32_e32 vcc, s72, v113
	v_add_u32_e32 v113, 0xffffffa7, v112
	s_nop 0
	v_cndmask_b32_e32 v44, v194, v44, vcc
	v_cmp_gt_u32_e32 vcc, s72, v113
	v_add_u32_e32 v113, 0xffffff87, v112
	s_nop 0
	v_cndmask_b32_e32 v61, v194, v61, vcc
	v_cmp_gt_u32_e32 vcc, s72, v113
	v_add_u32_e32 v113, 0xffffffa6, v112
	s_nop 0
	v_cndmask_b32_e32 v45, v194, v45, vcc
	v_cmp_gt_u32_e32 vcc, s72, v113
	v_add_u32_e32 v113, 0xffffff86, v112
	s_nop 0
	v_cndmask_b32_e32 v62, v194, v62, vcc
	v_cmp_gt_u32_e32 vcc, s72, v113
	v_add_u32_e32 v113, 0xffffffa5, v112
	v_add_u32_e32 v112, 0xffffff85, v112
	v_cndmask_b32_e32 v46, v194, v46, vcc
	v_cmp_gt_u32_e32 vcc, s72, v113
	s_nop 1
	v_cndmask_b32_e32 v63, v194, v63, vcc
	v_cmp_gt_u32_e32 vcc, s72, v112
	s_nop 1
	v_cndmask_b32_e32 v47, v194, v47, vcc

; #define MFMA(a, b, c) __builtin_amdgcn_mfma_f32_32x32x16_bf16((a), (b), (c), 0, 0, 0)
; DI int crow(int r, int hi) { return (r & 3) + 8 * (r >> 2) + 4 * hi; }
; template <class MaskF>
; DI void attn_tile(const int tid, const char* ldsK, const char* ldsV, const bf16x8 (&qr)[4], f32x16 (&o)[2], float& m, float& l, const bool MASKED, MaskF mask) {
;     ...
;   const char* kp = ldsK + l31 * 144 + hi * 16;
; #pragma unroll
;   for (int s = 0; s < 4; ++s) {
;     const bf16x8 k0 = *(const bf16x8*)(kp + s * 32), k1 = *(const bf16x8*)(kp + 32 * 144 + s * 32);
;     p0 = MFMA(k0, qr[s], p0); p1 = MFMA(k1, qr[s], p1);
;   }
;   if (MASKED) {
; #pragma unroll
;     for (int r = 0; r < 16; ++r) {
;       const int kr = crow(r, hi);
;       p0[r] = mask(kr) ? p0[r] : NEGB; p1[r] = mask(kr + 32) ? p1[r] : NEGB;
;     }
;   }
; DI void win_item(const Params& p, int it, char* lds) {
;     ...
;               [&](int ti, int kr) { return (unsigned)(t - ((klo + ti) * 64 + kr)) <= 511u; },
.LBB0_255:
	ds_read_b128 v[32:35], v161 offset:4608
	ds_read_b128 v[36:39], v161
	ds_read_b128 v[112:115], v161 offset:32
	ds_read_b128 v[116:119], v161 offset:4640
	ds_read_b128 v[120:123], v161 offset:64
	ds_read_b128 v[124:127], v161 offset:4672
	ds_read_b128 v[128:131], v161 offset:96
	ds_read_b128 v[132:135], v161 offset:4704
	s_add_i32 s11, s4, 0xffffff81
	s_sub_i32 s2, s4, 64
	s_waitcnt lgkmcnt(6)
	s_setprio 1
	v_mfma_f32_32x32x16_bf16 v[48:63], v[36:39], v[64:67], 0
	s_cmp_gt_u32 s2, s5
	s_cselect_b64 s[2:3], -1, 0
	s_cmp_lt_i32 s11, s9
	s_cselect_b64 s[12:13], -1, 0
	s_or_b64 s[2:3], s[2:3], s[12:13]
	s_andn2_b64 vcc, exec, s[2:3]
	v_mfma_f32_32x32x16_bf16 v[32:47], v[32:35], v[64:67], 0
	s_waitcnt lgkmcnt(5)
	v_mfma_f32_32x32x16_bf16 v[48:63], v[112:115], v[68:71], v[48:63]
	s_waitcnt lgkmcnt(4)
	v_mfma_f32_32x32x16_bf16 v[32:47], v[116:119], v[68:71], v[32:47]
	s_waitcnt lgkmcnt(3)
	v_mfma_f32_32x32x16_bf16 v[48:63], v[120:123], v[72:75], v[48:63]
	s_waitcnt lgkmcnt(2)
	v_mfma_f32_32x32x16_bf16 v[32:47], v[124:127], v[72:75], v[32:47]
	s_waitcnt lgkmcnt(1)
	v_mfma_f32_32x32x16_bf16 v[48:63], v[128:131], v[76:79], v[48:63]
	s_waitcnt lgkmcnt(0)
	v_mfma_f32_32x32x16_bf16 v[32:47], v[132:135], v[76:79], v[32:47]
	s_setprio 0
	s_cbranch_vccnz .LBB0_257
	v_add_u32_e32 v112, v150, v156
	v_cmp_gt_u32_e32 vcc, s72, v112
	v_subrev_u32_e32 v113, 32, v112
	s_nop 5
	v_cndmask_b32_e32 v48, v194, v48, vcc
	v_cmp_gt_u32_e32 vcc, s72, v113
	v_add_u32_e32 v113, -1, v112
	s_nop 0
	v_cndmask_b32_e32 v32, v194, v32, vcc
	v_cmp_gt_u32_e32 vcc, s72, v113
	v_subrev_u32_e32 v113, 33, v112
	s_nop 0
	v_cndmask_b32_e32 v49, v194, v49, vcc
	v_cmp_gt_u32_e32 vcc, s72, v113
	v_add_u32_e32 v113, -2, v112
	s_nop 0
	v_cndmask_b32_e32 v33, v194, v33, vcc
	v_cmp_gt_u32_e32 vcc, s72, v113
	v_subrev_u32_e32 v113, 34, v112
	s_nop 0
	v_cndmask_b32_e32 v50, v194, v50, vcc
	v_cmp_gt_u32_e32 vcc, s72, v113
	v_add_u32_e32 v113, -3, v112
	s_nop 0
	v_cndmask_b32_e32 v34, v194, v34, vcc
	v_cmp_gt_u32_e32 vcc, s72, v113
	v_subrev_u32_e32 v113, 35, v112
	s_nop 0
	v_cndmask_b32_e32 v51, v194, v51, vcc
	v_cmp_gt_u32_e32 vcc, s72, v113
	v_add_u32_e32 v113, -8, v112
	s_nop 0
	v_cndmask_b32_e32 v35, v194, v35, vcc
	v_cmp_gt_u32_e32 vcc, s72, v113
	v_subrev_u32_e32 v113, 40, v112
	s_nop 0
	v_cndmask_b32_e32 v52, v194, v52, vcc
	v_cmp_gt_u32_e32 vcc, s72, v113
	v_add_u32_e32 v113, -9, v112
	s_nop 0
	v_cndmask_b32_e32 v36, v194, v36, vcc
	v_cmp_gt_u32_e32 vcc, s72, v113
	v_subrev_u32_e32 v113, 41, v112
	s_nop 0
	v_cndmask_b32_e32 v53, v194, v53, vcc
	v_cmp_gt_u32_e32 vcc, s72, v113
	v_add_u32_e32 v113, -10, v112
	s_nop 0
	v_cndmask_b32_e32 v37, v194, v37, vcc
	v_cmp_gt_u32_e32 vcc, s72, v113
	v_subrev_u32_e32 v113, 42, v112
	s_nop 0
	v_cndmask_b32_e32 v54, v194, v54, vcc
	v_cmp_gt_u32_e32 vcc, s72, v113
	v_add_u32_e32 v113, -11, v112
	s_nop 0
	v_cndmask_b32_e32 v38, v194, v38, vcc
	v_cmp_gt_u32_e32 vcc, s72, v113
	v_subrev_u32_e32 v113, 43, v112
	s_nop 0
	v_cndmask_b32_e32 v55, v194, v55, vcc
	v_cmp_gt_u32_e32 vcc, s72, v113
	v_add_u32_e32 v113, -16, v112
	s_nop 0
	v_cndmask_b32_e32 v39, v194, v39, vcc
	v_cmp_gt_u32_e32 vcc, s72, v113
	v_subrev_u32_e32 v113, 48, v112
	s_nop 0
	v_cndmask_b32_e32 v56, v194, v56, vcc
	v_cmp_gt_u32_e32 vcc, s72, v113
	v_subrev_u32_e32 v113, 17, v112
	s_nop 0
	v_cndmask_b32_e32 v40, v194, v40, vcc
	v_cmp_gt_u32_e32 vcc, s72, v113
	v_subrev_u32_e32 v113, 49, v112
	s_nop 0
	v_cndmask_b32_e32 v57, v194, v57, vcc
	v_cmp_gt_u32_e32 vcc, s72, v113
	v_subrev_u32_e32 v113, 18, v112
	s_nop 0
	v_cndmask_b32_e32 v41, v194, v41, vcc
	v_cmp_gt_u32_e32 vcc, s72, v113
	v_subrev_u32_e32 v113, 50, v112
	s_nop 0
	v_cndmask_b32_e32 v58, v194, v58, vcc
	v_cmp_gt_u32_e32 vcc, s72, v113
	v_subrev_u32_e32 v113, 19, v112
	s_nop 0
	v_cndmask_b32_e32 v42, v194, v42, vcc
	v_cmp_gt_u32_e32 vcc, s72, v113
	v_subrev_u32_e32 v113, 51, v112
	s_nop 0
	v_cndmask_b32_e32 v59, v194, v59, vcc
	v_cmp_gt_u32_e32 vcc, s72, v113
	v_subrev_u32_e32 v113, 24, v112
	s_nop 0
	v_cndmask_b32_e32 v43, v194, v43, vcc
	v_cmp_gt_u32_e32 vcc, s72, v113
	v_subrev_u32_e32 v113, 56, v112
	s_nop 0
	v_cndmask_b32_e32 v60, v194, v60, vcc
	v_cmp_gt_u32_e32 vcc, s72, v113
	v_subrev_u32_e32 v113, 25, v112
	s_nop 0
	v_cndmask_b32_e32 v44, v194, v44, vcc
	v_cmp_gt_u32_e32 vcc, s72, v113
	v_subrev_u32_e32 v113, 57, v112
	s_nop 0
	v_cndmask_b32_e32 v61, v194, v61, vcc
	v_cmp_gt_u32_e32 vcc, s72, v113
	v_subrev_u32_e32 v113, 26, v112
	s_nop 0
	v_cndmask_b32_e32 v45, v194, v45, vcc
	v_cmp_gt_u32_e32 vcc, s72, v113
	v_subrev_u32_e32 v113, 58, v112
	s_nop 0
	v_cndmask_b32_e32 v62, v194, v62, vcc
	v_cmp_gt_u32_e32 vcc, s72, v113
	v_subrev_u32_e32 v113, 27, v112
	v_subrev_u32_e32 v112, 59, v112
	v_cndmask_b32_e32 v46, v194, v46, vcc
	v_cmp_gt_u32_e32 vcc, s72, v113
	s_nop 1
	v_cndmask_b32_e32 v63, v194, v63, vcc
	v_cmp_gt_u32_e32 vcc, s72, v112
	s_nop 1
	v_cndmask_b32_e32 v47, v194, v47, vcc

; #define MFMA(a, b, c) __builtin_amdgcn_mfma_f32_32x32x16_bf16((a), (b), (c), 0, 0, 0)
; DI int crow(int r, int hi) { return (r & 3) + 8 * (r >> 2) + 4 * hi; }
; template <class MaskF>
; DI void attn_tile(const int tid, const char* ldsK, const char* ldsV, const bf16x8 (&qr)[4], f32x16 (&o)[2], float& m, float& l, const bool MASKED, MaskF mask) {
;     ...
;   const char* kp = ldsK + l31 * 144 + hi * 16;
; #pragma unroll
;   for (int s = 0; s < 4; ++s) {
;     const bf16x8 k0 = *(const bf16x8*)(kp + s * 32), k1 = *(const bf16x8*)(kp + 32 * 144 + s * 32);
;     p0 = MFMA(k0, qr[s], p0); p1 = MFMA(k1, qr[s], p1);
;   }
;   if (MASKED) {
; #pragma unroll
;     for (int r = 0; r < 16; ++r) {
;       const int kr = crow(r, hi);
;       p0[r] = mask(kr) ? p0[r] : NEGB; p1[r] = mask(kr + 32) ? p1[r] : NEGB;
;     }
;   }
; DI void win_item(const Params& p, int it, char* lds) {
;     ...
;               [&](int ti, int kr) { return (unsigned)(t - ((klo + ti) * 64 + kr)) <= 511u; },
.LBB0_262:
	ds_read_b128 v[32:35], v161 offset:23040
	ds_read_b128 v[36:39], v161 offset:18432
	ds_read_b128 v[112:115], v161 offset:18464
	ds_read_b128 v[116:119], v161 offset:23072
	ds_read_b128 v[120:123], v161 offset:18496
	ds_read_b128 v[124:127], v161 offset:23104
	ds_read_b128 v[128:131], v161 offset:18528
	ds_read_b128 v[132:135], v161 offset:23136
	s_sub_i32 s11, s4, 63
	s_cmp_gt_u32 s4, s5
	s_waitcnt lgkmcnt(6)
	s_setprio 1
	v_mfma_f32_32x32x16_bf16 v[48:63], v[36:39], v[64:67], 0
	s_cselect_b64 s[2:3], -1, 0
	s_cmp_lt_i32 s11, s9
	s_cselect_b64 s[12:13], -1, 0
	s_or_b64 s[2:3], s[2:3], s[12:13]
	s_andn2_b64 vcc, exec, s[2:3]
	v_mfma_f32_32x32x16_bf16 v[32:47], v[32:35], v[64:67], 0
	s_waitcnt lgkmcnt(5)
	v_mfma_f32_32x32x16_bf16 v[48:63], v[112:115], v[68:71], v[48:63]
	s_waitcnt lgkmcnt(4)
	v_mfma_f32_32x32x16_bf16 v[32:47], v[116:119], v[68:71], v[32:47]
	s_waitcnt lgkmcnt(3)
	v_mfma_f32_32x32x16_bf16 v[48:63], v[120:123], v[72:75], v[48:63]
	s_waitcnt lgkmcnt(2)
	v_mfma_f32_32x32x16_bf16 v[32:47], v[124:127], v[72:75], v[32:47]
	s_waitcnt lgkmcnt(1)
	v_mfma_f32_32x32x16_bf16 v[48:63], v[128:131], v[76:79], v[48:63]
	s_waitcnt lgkmcnt(0)
	v_mfma_f32_32x32x16_bf16 v[32:47], v[132:135], v[76:79], v[32:47]
	s_setprio 0
	s_cbranch_vccnz .LBB0_264
	v_add_u32_e32 v112, v150, v155
	v_subrev_u32_e32 v113, 64, v112
	v_cmp_gt_u32_e32 vcc, s72, v113
	v_add_u32_e32 v113, 0xffffffa0, v112
	s_nop 4
	v_cndmask_b32_e32 v48, v194, v48, vcc
	v_cmp_gt_u32_e32 vcc, s72, v113
	v_add_u32_e32 v113, 0xffffffbf, v112
	s_nop 0
	v_cndmask_b32_e32 v32, v194, v32, vcc
	v_cmp_gt_u32_e32 vcc, s72, v113
	v_add_u32_e32 v113, 0xffffff9f, v112
	s_nop 0
	v_cndmask_b32_e32 v49, v194, v49, vcc
	v_cmp_gt_u32_e32 vcc, s72, v113
	v_add_u32_e32 v113, 0xffffffbe, v112
	s_nop 0
	v_cndmask_b32_e32 v33, v194, v33, vcc
	v_cmp_gt_u32_e32 vcc, s72, v113
	v_add_u32_e32 v113, 0xffffff9e, v112
	s_nop 0
	v_cndmask_b32_e32 v50, v194, v50, vcc
	v_cmp_gt_u32_e32 vcc, s72, v113
	v_add_u32_e32 v113, 0xffffffbd, v112
	s_nop 0
	v_cndmask_b32_e32 v34, v194, v34, vcc
	v_cmp_gt_u32_e32 vcc, s72, v113
	v_add_u32_e32 v113, 0xffffff9d, v112
	s_nop 0
	v_cndmask_b32_e32 v51, v194, v51, vcc
	v_cmp_gt_u32_e32 vcc, s72, v113
	v_add_u32_e32 v113, 0xffffffb8, v112
	s_nop 0
	v_cndmask_b32_e32 v35, v194, v35, vcc
	v_cmp_gt_u32_e32 vcc, s72, v113
	v_add_u32_e32 v113, 0xffffff98, v112
	s_nop 0
	v_cndmask_b32_e32 v52, v194, v52, vcc
	v_cmp_gt_u32_e32 vcc, s72, v113
	v_add_u32_e32 v113, 0xffffffb7, v112
	s_nop 0
	v_cndmask_b32_e32 v36, v194, v36, vcc
	v_cmp_gt_u32_e32 vcc, s72, v113
	v_add_u32_e32 v113, 0xffffff97, v112
	s_nop 0
	v_cndmask_b32_e32 v53, v194, v53, vcc
	v_cmp_gt_u32_e32 vcc, s72, v113
	v_add_u32_e32 v113, 0xffffffb6, v112
	s_nop 0
	v_cndmask_b32_e32 v37, v194, v37, vcc
	v_cmp_gt_u32_e32 vcc, s72, v113
	v_add_u32_e32 v113, 0xffffff96, v112
	s_nop 0
	v_cndmask_b32_e32 v54, v194, v54, vcc
	v_cmp_gt_u32_e32 vcc, s72, v113
	v_add_u32_e32 v113, 0xffffffb5, v112
	s_nop 0
	v_cndmask_b32_e32 v38, v194, v38, vcc
	v_cmp_gt_u32_e32 vcc, s72, v113
	v_add_u32_e32 v113, 0xffffff95, v112
	s_nop 0
	v_cndmask_b32_e32 v55, v194, v55, vcc
	v_cmp_gt_u32_e32 vcc, s72, v113
	v_add_u32_e32 v113, 0xffffffb0, v112
	s_nop 0
	v_cndmask_b32_e32 v39, v194, v39, vcc
	v_cmp_gt_u32_e32 vcc, s72, v113
	v_add_u32_e32 v113, 0xffffff90, v112
	s_nop 0
	v_cndmask_b32_e32 v56, v194, v56, vcc
	v_cmp_gt_u32_e32 vcc, s72, v113
	v_add_u32_e32 v113, 0xffffffaf, v112
	s_nop 0
	v_cndmask_b32_e32 v40, v194, v40, vcc
	v_cmp_gt_u32_e32 vcc, s72, v113
	v_add_u32_e32 v113, 0xffffff8f, v112
	s_nop 0
	v_cndmask_b32_e32 v57, v194, v57, vcc
	v_cmp_gt_u32_e32 vcc, s72, v113
	v_add_u32_e32 v113, 0xffffffae, v112
	s_nop 0
	v_cndmask_b32_e32 v41, v194, v41, vcc
	v_cmp_gt_u32_e32 vcc, s72, v113
	v_add_u32_e32 v113, 0xffffff8e, v112
	s_nop 0
	v_cndmask_b32_e32 v58, v194, v58, vcc
	v_cmp_gt_u32_e32 vcc, s72, v113
	v_add_u32_e32 v113, 0xffffffad, v112
	s_nop 0
	v_cndmask_b32_e32 v42, v194, v42, vcc
	v_cmp_gt_u32_e32 vcc, s72, v113
	v_add_u32_e32 v113, 0xffffff8d, v112
	s_nop 0
	v_cndmask_b32_e32 v59, v194, v59, vcc
	v_cmp_gt_u32_e32 vcc, s72, v113
	v_add_u32_e32 v113, 0xffffffa8, v112
	s_nop 0
	v_cndmask_b32_e32 v43, v194, v43, vcc
	v_cmp_gt_u32_e32 vcc, s72, v113
	v_add_u32_e32 v113, 0xffffff88, v112
	s_nop 0
	v_cndmask_b32_e32 v60, v194, v60, vcc
	v_cmp_gt_u32_e32 vcc, s72, v113
	v_add_u32_e32 v113, 0xffffffa7, v112
	s_nop 0
	v_cndmask_b32_e32 v44, v194, v44, vcc
	v_cmp_gt_u32_e32 vcc, s72, v113
	v_add_u32_e32 v113, 0xffffff87, v112
	s_nop 0
	v_cndmask_b32_e32 v61, v194, v61, vcc
	v_cmp_gt_u32_e32 vcc, s72, v113
	v_add_u32_e32 v113, 0xffffffa6, v112
	s_nop 0
	v_cndmask_b32_e32 v45, v194, v45, vcc
	v_cmp_gt_u32_e32 vcc, s72, v113
	v_add_u32_e32 v113, 0xffffff86, v112
	s_nop 0
	v_cndmask_b32_e32 v62, v194, v62, vcc
	v_cmp_gt_u32_e32 vcc, s72, v113
	v_add_u32_e32 v113, 0xffffffa5, v112
	v_add_u32_e32 v112, 0xffffff85, v112
	v_cndmask_b32_e32 v46, v194, v46, vcc
	v_cmp_gt_u32_e32 vcc, s72, v113
	s_nop 1
	v_cndmask_b32_e32 v63, v194, v63, vcc
	v_cmp_gt_u32_e32 vcc, s72, v112
	s_nop 1
	v_cndmask_b32_e32 v47, v194, v47, vcc

; #define MFMA(a, b, c) __builtin_amdgcn_mfma_f32_32x32x16_bf16((a), (b), (c), 0, 0, 0)
; DI int crow(int r, int hi) { return (r & 3) + 8 * (r >> 2) + 4 * hi; }
; template <class MaskF>
; DI void attn_tile(const int tid, const char* ldsK, const char* ldsV, const bf16x8 (&qr)[4], f32x16 (&o)[2], float& m, float& l, const bool MASKED, MaskF mask) {
;     ...
;   const char* kp = ldsK + l31 * 144 + hi * 16;
; #pragma unroll
;   for (int s = 0; s < 4; ++s) {
;     const bf16x8 k0 = *(const bf16x8*)(kp + s * 32), k1 = *(const bf16x8*)(kp + 32 * 144 + s * 32);
;     p0 = MFMA(k0, qr[s], p0); p1 = MFMA(k1, qr[s], p1);
;   }
;   if (MASKED) {
; #pragma unroll
;     for (int r = 0; r < 16; ++r) {
;       const int kr = crow(r, hi);
;       p0[r] = mask(kr) ? p0[r] : NEGB; p1[r] = mask(kr + 32) ? p1[r] : NEGB;
;     }
;   }
; DI void dil_item(const Params& p, int it, char* lds) {
;     ...
;   for (int tt = tt0; tt < 4; ++tt) {
;     const int tk0 = m0 - 128 + 64 * tt;
;     if (tk0 + 63 >= wlo && tk0 <= whi) {
;       attn_tile(tid, lds + tt * 18432, lds + tt * 18432 + 9216, qr, o, m, lsum, !(tk0 + 63 <= wlo + 128 && tk0 >= whi - 128), [&](int kr) { return (unsigned)(mq - (tk0 + kr)) <= 128u; });
.LBB0_277:
	s_add_i32 s13, s12, 63
	s_cmp_lt_i32 s13, s1
	s_cselect_b64 s[14:15], -1, 0
	s_cmp_gt_i32 s12, s3
	s_cselect_b64 s[16:17], -1, 0
	s_or_b64 s[14:15], s[14:15], s[16:17]
	s_and_b64 vcc, exec, s[14:15]
	s_cbranch_vccnz .LBB0_276
	v_add_u32_e32 v88, s7, v118
	ds_read_b128 v[32:35], v88 offset:4608
	ds_read_b128 v[36:39], v88
	ds_read_b128 v[80:83], v88 offset:32
	ds_read_b128 v[84:87], v88 offset:4640
	ds_read_b128 v[124:127], v88 offset:64
	ds_read_b128 v[128:131], v88 offset:4672
	ds_read_b128 v[132:135], v88 offset:96
	ds_read_b128 v[136:139], v88 offset:4704
	s_cmp_gt_i32 s13, s0
	s_cselect_b64 s[14:15], -1, 0
	s_waitcnt lgkmcnt(6)
	s_setprio 1
	v_mfma_f32_32x32x16_bf16 v[48:63], v[36:39], v[64:67], 0
	s_cmp_lt_i32 s12, s5
	s_cselect_b64 s[16:17], -1, 0
	s_or_b64 s[14:15], s[14:15], s[16:17]
	s_andn2_b64 vcc, exec, s[14:15]
	v_mfma_f32_32x32x16_bf16 v[32:47], v[32:35], v[64:67], 0
	s_waitcnt lgkmcnt(5)
	v_mfma_f32_32x32x16_bf16 v[48:63], v[80:83], v[68:71], v[48:63]
	s_waitcnt lgkmcnt(4)
	v_mfma_f32_32x32x16_bf16 v[32:47], v[84:87], v[68:71], v[32:47]
	s_waitcnt lgkmcnt(3)
	v_mfma_f32_32x32x16_bf16 v[48:63], v[124:127], v[72:75], v[48:63]
	s_waitcnt lgkmcnt(2)
	v_mfma_f32_32x32x16_bf16 v[32:47], v[128:131], v[72:75], v[32:47]
	s_waitcnt lgkmcnt(1)
	v_mfma_f32_32x32x16_bf16 v[48:63], v[132:135], v[76:79], v[48:63]
	s_waitcnt lgkmcnt(0)
	v_mfma_f32_32x32x16_bf16 v[32:47], v[136:139], v[76:79], v[32:47]
	s_setprio 0
	s_cbranch_vccnz .LBB0_280
	v_cmp_gt_u32_e32 vcc, s85, v120
	v_subrev_u32_e32 v80, 32, v120
	s_nop 6
	v_cndmask_b32_e32 v48, v194, v48, vcc
	v_cmp_gt_u32_e32 vcc, s85, v80
	v_add_u32_e32 v80, -1, v120
	s_nop 0
	v_cndmask_b32_e32 v32, v194, v32, vcc
	v_cmp_gt_u32_e32 vcc, s85, v80
	v_subrev_u32_e32 v80, 33, v120
	s_nop 0
	v_cndmask_b32_e32 v49, v194, v49, vcc
	v_cmp_gt_u32_e32 vcc, s85, v80
	v_add_u32_e32 v80, -2, v120
	s_nop 0
	v_cndmask_b32_e32 v33, v194, v33, vcc
	v_cmp_gt_u32_e32 vcc, s85, v80
	v_subrev_u32_e32 v80, 34, v120
	s_nop 0
	v_cndmask_b32_e32 v50, v194, v50, vcc
	v_cmp_gt_u32_e32 vcc, s85, v80
	v_add_u32_e32 v80, -3, v120
	s_nop 0
	v_cndmask_b32_e32 v34, v194, v34, vcc
	v_cmp_gt_u32_e32 vcc, s85, v80
	v_subrev_u32_e32 v80, 35, v120
	s_nop 0
	v_cndmask_b32_e32 v51, v194, v51, vcc
	v_cmp_gt_u32_e32 vcc, s85, v80
	v_add_u32_e32 v80, -8, v120
	s_nop 0
	v_cndmask_b32_e32 v35, v194, v35, vcc
	v_cmp_gt_u32_e32 vcc, s85, v80
	v_subrev_u32_e32 v80, 40, v120
	s_nop 0
	v_cndmask_b32_e32 v52, v194, v52, vcc
	v_cmp_gt_u32_e32 vcc, s85, v80
	v_add_u32_e32 v80, -9, v120
	s_nop 0
	v_cndmask_b32_e32 v36, v194, v36, vcc
	v_cmp_gt_u32_e32 vcc, s85, v80
	v_subrev_u32_e32 v80, 41, v120
	s_nop 0
	v_cndmask_b32_e32 v53, v194, v53, vcc
	v_cmp_gt_u32_e32 vcc, s85, v80
	v_add_u32_e32 v80, -10, v120
	s_nop 0
	v_cndmask_b32_e32 v37, v194, v37, vcc
	v_cmp_gt_u32_e32 vcc, s85, v80
	v_subrev_u32_e32 v80, 42, v120
	s_nop 0
	v_cndmask_b32_e32 v54, v194, v54, vcc
	v_cmp_gt_u32_e32 vcc, s85, v80
	v_add_u32_e32 v80, -11, v120
	s_nop 0
	v_cndmask_b32_e32 v38, v194, v38, vcc
	v_cmp_gt_u32_e32 vcc, s85, v80
	v_subrev_u32_e32 v80, 43, v120
	s_nop 0
	v_cndmask_b32_e32 v55, v194, v55, vcc
	v_cmp_gt_u32_e32 vcc, s85, v80
	v_add_u32_e32 v80, -16, v120
	s_nop 0
	v_cndmask_b32_e32 v39, v194, v39, vcc
	v_cmp_gt_u32_e32 vcc, s85, v80
	v_subrev_u32_e32 v80, 48, v120
	s_nop 0
	v_cndmask_b32_e32 v56, v194, v56, vcc
	v_cmp_gt_u32_e32 vcc, s85, v80
	v_subrev_u32_e32 v80, 17, v120
	s_nop 0
	v_cndmask_b32_e32 v40, v194, v40, vcc
	v_cmp_gt_u32_e32 vcc, s85, v80
	v_subrev_u32_e32 v80, 49, v120
	s_nop 0
	v_cndmask_b32_e32 v57, v194, v57, vcc
	v_cmp_gt_u32_e32 vcc, s85, v80
	v_subrev_u32_e32 v80, 18, v120
	s_nop 0
	v_cndmask_b32_e32 v41, v194, v41, vcc
	v_cmp_gt_u32_e32 vcc, s85, v80
	v_subrev_u32_e32 v80, 50, v120
	s_nop 0
	v_cndmask_b32_e32 v58, v194, v58, vcc
	v_cmp_gt_u32_e32 vcc, s85, v80
	v_subrev_u32_e32 v80, 19, v120
	s_nop 0
	v_cndmask_b32_e32 v42, v194, v42, vcc
	v_cmp_gt_u32_e32 vcc, s85, v80
	v_subrev_u32_e32 v80, 51, v120
	s_nop 0
	v_cndmask_b32_e32 v59, v194, v59, vcc
	v_cmp_gt_u32_e32 vcc, s85, v80
	v_subrev_u32_e32 v80, 24, v120
	s_nop 0
	v_cndmask_b32_e32 v43, v194, v43, vcc
	v_cmp_gt_u32_e32 vcc, s85, v80
	v_subrev_u32_e32 v80, 56, v120
	s_nop 0
	v_cndmask_b32_e32 v60, v194, v60, vcc
	v_cmp_gt_u32_e32 vcc, s85, v80
	v_subrev_u32_e32 v80, 25, v120
	s_nop 0
	v_cndmask_b32_e32 v44, v194, v44, vcc
	v_cmp_gt_u32_e32 vcc, s85, v80
	v_subrev_u32_e32 v80, 57, v120
	s_nop 0
	v_cndmask_b32_e32 v61, v194, v61, vcc
	v_cmp_gt_u32_e32 vcc, s85, v80
	v_subrev_u32_e32 v80, 26, v120
	s_nop 0
	v_cndmask_b32_e32 v45, v194, v45, vcc
	v_cmp_gt_u32_e32 vcc, s85, v80
	v_subrev_u32_e32 v80, 58, v120
	s_nop 0
	v_cndmask_b32_e32 v62, v194, v62, vcc
	v_cmp_gt_u32_e32 vcc, s85, v80
	v_subrev_u32_e32 v80, 27, v120
	s_nop 0
	v_cndmask_b32_e32 v46, v194, v46, vcc
	v_cmp_gt_u32_e32 vcc, s85, v80
	v_subrev_u32_e32 v80, 59, v120
	s_nop 0
	v_cndmask_b32_e32 v63, v194, v63, vcc
	v_cmp_gt_u32_e32 vcc, s85, v80
	s_nop 1
	v_cndmask_b32_e32 v47, v194, v47, vcc

; #define MFMA(a, b, c) __builtin_amdgcn_mfma_f32_32x32x16_bf16((a), (b), (c), 0, 0, 0)
; DI int crow(int r, int hi) { return (r & 3) + 8 * (r >> 2) + 4 * hi; }
; template <class MaskF>
; DI void attn_tile(const int tid, const char* ldsK, const char* ldsV, const bf16x8 (&qr)[4], f32x16 (&o)[2], float& m, float& l, const bool MASKED, MaskF mask) {
;     ...
;   const char* kp = ldsK + l31 * 144 + hi * 16;
; #pragma unroll
;   for (int s = 0; s < 4; ++s) {
;     const bf16x8 k0 = *(const bf16x8*)(kp + s * 32), k1 = *(const bf16x8*)(kp + 32 * 144 + s * 32);
;     p0 = MFMA(k0, qr[s], p0); p1 = MFMA(k1, qr[s], p1);
;   }
;   if (MASKED) {
; #pragma unroll
;     for (int r = 0; r < 16; ++r) {
;       const int kr = crow(r, hi);
;       p0[r] = mask(kr) ? p0[r] : NEGB; p1[r] = mask(kr + 32) ? p1[r] : NEGB;
;     }
;   }
; DI void nsa_item(const Params& p, int it, char* lds) {
;     ...
;               [&](int ti) { const int jb = jlist[ti]; return (jb < cur) && ((allm >> jb) & 1u); },
;               [&](int ti, int kr) { const int jb = jlist[ti]; return ((mymask >> jb) & 1u) && (jb * 64 + kr <= t); },
.LBB0_475:
	ds_read_b128 v[32:35], v219
	ds_read_b128 v[112:115], v219 offset:32
	ds_read_b128 v[124:127], v219 offset:4608
	ds_read_b128 v[116:119], v219 offset:96
	ds_read_b128 v[128:131], v219 offset:4640
	ds_read_b128 v[132:135], v219 offset:64
	ds_read_b128 v[136:139], v219 offset:4672
	ds_read_b128 v[140:143], v219 offset:4704
	v_mov_b32_e32 v120, s5
	s_waitcnt lgkmcnt(7)
	s_setprio 1
	v_mfma_f32_32x32x16_bf16 v[48:63], v[32:35], v[64:67], 0
	s_waitcnt lgkmcnt(6)
	v_mfma_f32_32x32x16_bf16 v[48:63], v[112:115], v[68:71], v[48:63]
	s_waitcnt lgkmcnt(5)
	v_mfma_f32_32x32x16_bf16 v[32:47], v[124:127], v[64:67], 0
	s_waitcnt lgkmcnt(3)
	v_mfma_f32_32x32x16_bf16 v[32:47], v[128:131], v[68:71], v[32:47]
	s_waitcnt lgkmcnt(2)
	v_mfma_f32_32x32x16_bf16 v[48:63], v[132:135], v[72:75], v[48:63]
	s_waitcnt lgkmcnt(1)
	v_mfma_f32_32x32x16_bf16 v[32:47], v[136:139], v[72:75], v[32:47]
	ds_read_b32 v112, v120
	s_waitcnt lgkmcnt(0)
	v_lshlrev_b32_e64 v113, v112, 1
	v_and_b32_e32 v114, s2, v113
	v_mfma_f32_32x32x16_bf16 v[48:63], v[116:119], v[76:79], v[48:63]
	v_cmp_le_i32_e32 vcc, s36, v112
	v_cmp_eq_u32_e64 s[0:1], 0, v114
	s_or_b64 s[0:1], vcc, s[0:1]
	s_andn2_b64 vcc, exec, s[0:1]
	v_mfma_f32_32x32x16_bf16 v[32:47], v[140:143], v[76:79], v[32:47]
	s_setprio 0
	s_cbranch_vccnz .LBB0_477
	v_and_b32_e32 v113, v113, v166
	v_lshlrev_b32_e32 v112, 6, v112
	v_cmp_ne_u32_e32 vcc, 0, v113
	v_sub_u32_e32 v113, v147, v112
	s_nop 0
	v_cndmask_b32_e32 v113, -1, v113, vcc
	v_cmp_ge_i32_e64 s[0:1], v113, v156
	v_cmp_ge_i32_e64 s[10:11], v113, v157
	v_cmp_ge_i32_e64 s[12:13], v113, v160
	v_cndmask_b32_e64 v48, v194, v48, s[0:1]
	v_cmp_ge_i32_e64 s[0:1], v113, v168
	v_cndmask_b32_e64 v32, v194, v32, s[10:11]
	v_cmp_ge_i32_e64 s[10:11], v113, v169
	v_cndmask_b32_e64 v49, v194, v49, s[12:13]
	v_cmp_ge_i32_e64 s[12:13], v113, v170
	v_cndmask_b32_e64 v33, v194, v33, s[0:1]
	v_cmp_ge_i32_e64 s[0:1], v113, v171
	v_cndmask_b32_e64 v50, v194, v50, s[10:11]
	v_cmp_ge_i32_e64 s[10:11], v113, v172
	v_cndmask_b32_e64 v34, v194, v34, s[12:13]
	v_cmp_ge_i32_e64 s[12:13], v113, v173
	v_cndmask_b32_e64 v51, v194, v51, s[0:1]
	v_cmp_ge_i32_e64 s[0:1], v113, v174
	v_cndmask_b32_e64 v35, v194, v35, s[10:11]
	v_cmp_ge_i32_e64 s[10:11], v113, v175
	v_cndmask_b32_e64 v52, v194, v52, s[12:13]
	v_cmp_ge_i32_e64 s[12:13], v113, v181
	v_cndmask_b32_e64 v36, v194, v36, s[0:1]
	v_cmp_ge_i32_e64 s[0:1], v113, v183
	v_cndmask_b32_e64 v53, v194, v53, s[10:11]
	v_cmp_ge_i32_e64 s[10:11], v113, v185
	v_cndmask_b32_e64 v37, v194, v37, s[12:13]
	v_cmp_ge_i32_e64 s[12:13], v113, v186
	v_cndmask_b32_e64 v54, v194, v54, s[0:1]
	v_cmp_ge_i32_e64 s[0:1], v113, v187
	v_cndmask_b32_e64 v38, v194, v38, s[10:11]
	v_cmp_ge_i32_e64 s[10:11], v113, v202
	v_cndmask_b32_e64 v55, v194, v55, s[12:13]
	v_cmp_ge_i32_e64 s[12:13], v113, v203
	v_cndmask_b32_e64 v39, v194, v39, s[0:1]
	v_cmp_ge_i32_e64 s[0:1], v113, v204
	v_cndmask_b32_e64 v56, v194, v56, s[10:11]
	v_cmp_ge_i32_e64 s[10:11], v113, v205
	v_cndmask_b32_e64 v40, v194, v40, s[12:13]
	v_cmp_ge_i32_e64 s[12:13], v113, v206
	v_cndmask_b32_e64 v57, v194, v57, s[0:1]
	v_cmp_ge_i32_e64 s[0:1], v113, v207
	v_cndmask_b32_e64 v41, v194, v41, s[10:11]
	v_cmp_ge_i32_e64 s[10:11], v113, v208
	v_cndmask_b32_e64 v58, v194, v58, s[12:13]
	v_cmp_ge_i32_e64 s[12:13], v113, v209
	v_cndmask_b32_e64 v42, v194, v42, s[0:1]
	v_cmp_ge_i32_e64 s[0:1], v113, v210
	v_cndmask_b32_e64 v59, v194, v59, s[10:11]
	v_cmp_ge_i32_e64 s[10:11], v113, v211
	v_cndmask_b32_e64 v43, v194, v43, s[12:13]
	v_cmp_ge_i32_e64 s[12:13], v113, v212
	v_cndmask_b32_e64 v60, v194, v60, s[0:1]
	v_cmp_ge_i32_e64 s[0:1], v113, v213
	v_cndmask_b32_e64 v44, v194, v44, s[10:11]
	v_cmp_ge_i32_e64 s[10:11], v113, v214
	v_cndmask_b32_e64 v61, v194, v61, s[12:13]
	v_cmp_ge_i32_e64 s[12:13], v113, v215
	v_cndmask_b32_e64 v45, v194, v45, s[0:1]
	v_cmp_ge_i32_e64 s[0:1], v113, v216
	v_cndmask_b32_e64 v62, v194, v62, s[10:11]
	v_cmp_ge_i32_e64 s[10:11], v113, v217
	v_cndmask_b32_e64 v46, v194, v46, s[12:13]
	v_cndmask_b32_e64 v63, v194, v63, s[0:1]
	v_cndmask_b32_e64 v47, v194, v47, s[10:11]

; #define MFMA(a, b, c) __builtin_amdgcn_mfma_f32_32x32x16_bf16((a), (b), (c), 0, 0, 0)
; DI int crow(int r, int hi) { return (r & 3) + 8 * (r >> 2) + 4 * hi; }
; template <class MaskF>
; DI void attn_tile(const int tid, const char* ldsK, const char* ldsV, const bf16x8 (&qr)[4], f32x16 (&o)[2], float& m, float& l, const bool MASKED, MaskF mask) {
;     ...
;   const char* kp = ldsK + l31 * 144 + hi * 16;
; #pragma unroll
;   for (int s = 0; s < 4; ++s) {
;     const bf16x8 k0 = *(const bf16x8*)(kp + s * 32), k1 = *(const bf16x8*)(kp + 32 * 144 + s * 32);
;     p0 = MFMA(k0, qr[s], p0); p1 = MFMA(k1, qr[s], p1);
;   }
;   if (MASKED) {
; #pragma unroll
;     for (int r = 0; r < 16; ++r) {
;       const int kr = crow(r, hi);
;       p0[r] = mask(kr) ? p0[r] : NEGB; p1[r] = mask(kr + 32) ? p1[r] : NEGB;
;     }
;   }
; DI void nsa_item(const Params& p, int it, char* lds) {
;     ...
;               [&](int ti) { const int jb = jlist[ti]; return (jb < cur) && ((allm >> jb) & 1u); },
;               [&](int ti, int kr) { const int jb = jlist[ti]; return ((mymask >> jb) & 1u) && (jb * 64 + kr <= t); },
.LBB0_482:
	ds_read_b128 v[32:35], v219 offset:18432
	ds_read_b128 v[112:115], v219 offset:18464
	ds_read_b128 v[124:127], v219 offset:23040
	ds_read_b128 v[116:119], v219 offset:18528
	ds_read_b128 v[128:131], v219 offset:23072
	ds_read_b128 v[132:135], v219 offset:18496
	ds_read_b128 v[136:139], v219 offset:23104
	ds_read_b128 v[140:143], v219 offset:23136
	v_mov_b32_e32 v120, s5
	s_waitcnt lgkmcnt(7)
	s_setprio 1
	v_mfma_f32_32x32x16_bf16 v[48:63], v[32:35], v[64:67], 0
	s_waitcnt lgkmcnt(6)
	v_mfma_f32_32x32x16_bf16 v[48:63], v[112:115], v[68:71], v[48:63]
	s_waitcnt lgkmcnt(5)
	v_mfma_f32_32x32x16_bf16 v[32:47], v[124:127], v[64:67], 0
	s_waitcnt lgkmcnt(3)
	v_mfma_f32_32x32x16_bf16 v[32:47], v[128:131], v[68:71], v[32:47]
	s_waitcnt lgkmcnt(2)
	v_mfma_f32_32x32x16_bf16 v[48:63], v[132:135], v[72:75], v[48:63]
	s_waitcnt lgkmcnt(1)
	v_mfma_f32_32x32x16_bf16 v[32:47], v[136:139], v[72:75], v[32:47]
	ds_read_b32 v112, v120 offset:4
	s_waitcnt lgkmcnt(0)
	v_lshlrev_b32_e64 v113, v112, 1
	v_and_b32_e32 v114, s2, v113
	v_mfma_f32_32x32x16_bf16 v[48:63], v[116:119], v[76:79], v[48:63]
	v_cmp_le_i32_e32 vcc, s36, v112
	v_cmp_eq_u32_e64 s[0:1], 0, v114
	s_or_b64 s[0:1], vcc, s[0:1]
	s_andn2_b64 vcc, exec, s[0:1]
	v_mfma_f32_32x32x16_bf16 v[32:47], v[140:143], v[76:79], v[32:47]
	s_setprio 0
	s_cbranch_vccnz .LBB0_484
	v_and_b32_e32 v113, v113, v166
	v_lshlrev_b32_e32 v112, 6, v112
	v_cmp_ne_u32_e32 vcc, 0, v113
	v_sub_u32_e32 v113, v147, v112
	s_nop 0
	v_cndmask_b32_e32 v113, -1, v113, vcc
	v_cmp_ge_i32_e64 s[0:1], v113, v156
	v_cmp_ge_i32_e64 s[10:11], v113, v157
	v_cmp_ge_i32_e64 s[12:13], v113, v160
	v_cndmask_b32_e64 v48, v194, v48, s[0:1]
	v_cmp_ge_i32_e64 s[0:1], v113, v168
	v_cndmask_b32_e64 v32, v194, v32, s[10:11]
	v_cmp_ge_i32_e64 s[10:11], v113, v169
	v_cndmask_b32_e64 v49, v194, v49, s[12:13]
	v_cmp_ge_i32_e64 s[12:13], v113, v170
	v_cndmask_b32_e64 v33, v194, v33, s[0:1]
	v_cmp_ge_i32_e64 s[0:1], v113, v171
	v_cndmask_b32_e64 v50, v194, v50, s[10:11]
	v_cmp_ge_i32_e64 s[10:11], v113, v172
	v_cndmask_b32_e64 v34, v194, v34, s[12:13]
	v_cmp_ge_i32_e64 s[12:13], v113, v173
	v_cndmask_b32_e64 v51, v194, v51, s[0:1]
	v_cmp_ge_i32_e64 s[0:1], v113, v174
	v_cndmask_b32_e64 v35, v194, v35, s[10:11]
	v_cmp_ge_i32_e64 s[10:11], v113, v175
	v_cndmask_b32_e64 v52, v194, v52, s[12:13]
	v_cmp_ge_i32_e64 s[12:13], v113, v181
	v_cndmask_b32_e64 v36, v194, v36, s[0:1]
	v_cmp_ge_i32_e64 s[0:1], v113, v183
	v_cndmask_b32_e64 v53, v194, v53, s[10:11]
	v_cmp_ge_i32_e64 s[10:11], v113, v185
	v_cndmask_b32_e64 v37, v194, v37, s[12:13]
	v_cmp_ge_i32_e64 s[12:13], v113, v186
	v_cndmask_b32_e64 v54, v194, v54, s[0:1]
	v_cmp_ge_i32_e64 s[0:1], v113, v187
	v_cndmask_b32_e64 v38, v194, v38, s[10:11]
	v_cmp_ge_i32_e64 s[10:11], v113, v202
	v_cndmask_b32_e64 v55, v194, v55, s[12:13]
	v_cmp_ge_i32_e64 s[12:13], v113, v203
	v_cndmask_b32_e64 v39, v194, v39, s[0:1]
	v_cmp_ge_i32_e64 s[0:1], v113, v204
	v_cndmask_b32_e64 v56, v194, v56, s[10:11]
	v_cmp_ge_i32_e64 s[10:11], v113, v205
	v_cndmask_b32_e64 v40, v194, v40, s[12:13]
	v_cmp_ge_i32_e64 s[12:13], v113, v206
	v_cndmask_b32_e64 v57, v194, v57, s[0:1]
	v_cmp_ge_i32_e64 s[0:1], v113, v207
	v_cndmask_b32_e64 v41, v194, v41, s[10:11]
	v_cmp_ge_i32_e64 s[10:11], v113, v208
	v_cndmask_b32_e64 v58, v194, v58, s[12:13]
	v_cmp_ge_i32_e64 s[12:13], v113, v209
	v_cndmask_b32_e64 v42, v194, v42, s[0:1]
	v_cmp_ge_i32_e64 s[0:1], v113, v210
	v_cndmask_b32_e64 v59, v194, v59, s[10:11]
	v_cmp_ge_i32_e64 s[10:11], v113, v211
	v_cndmask_b32_e64 v43, v194, v43, s[12:13]
	v_cmp_ge_i32_e64 s[12:13], v113, v212
	v_cndmask_b32_e64 v60, v194, v60, s[0:1]
	v_cmp_ge_i32_e64 s[0:1], v113, v213
	v_cndmask_b32_e64 v44, v194, v44, s[10:11]
	v_cmp_ge_i32_e64 s[10:11], v113, v214
	v_cndmask_b32_e64 v61, v194, v61, s[12:13]
	v_cmp_ge_i32_e64 s[12:13], v113, v215
	v_cndmask_b32_e64 v45, v194, v45, s[0:1]
	v_cmp_ge_i32_e64 s[0:1], v113, v216
	v_cndmask_b32_e64 v62, v194, v62, s[10:11]
	v_cmp_ge_i32_e64 s[10:11], v113, v217
	v_cndmask_b32_e64 v46, v194, v46, s[12:13]
	v_cndmask_b32_e64 v63, v194, v63, s[0:1]
	v_cndmask_b32_e64 v47, v194, v47, s[10:11]
